# attention without the static s_setprio 1 on waves 4-7
# speedup vs baseline: 1.0029x; 1.0029x over previous
; __device__ __forceinline__ int v_st(int k, int c) { const int kk = (k & ~0xC) | ((k & 4) << 1) | ((k & 8) >> 1); return ((kk >> 3) * 4 + (c >> 5)) * 512 + ((kk & 7) * 32 + (c & 31)) * 2; }
; __device__ __forceinline__ void attn_unit(const bf16* __restrict__ Qg, const bf16* __restrict__ KNg, const bf16* __restrict__ KRg, const bf16* __restrict__ Vg, bf16* __restrict__ AO, ...
;   int tid = threadIdx.x; asm volatile("" : "+v"(tid));
;   const int wid = __builtin_amdgcn_readfirstlane(tid >> 6), lane = tid & 63, r32 = lane & 31, hi = lane >> 5;
;   char* V_lds = lds + OFF_V; char* KN_lds = lds + OFF_KN; char* KR_lds = lds + OFF_KR;
;   float* ws = (float*)(lds + OFF_WS) + wid * 64; float* li_l = ws; float* al_l = ws + 32;
;   float mhat = 0.f, l_reg = 0; f32x16 negm = f32x16{}; asm volatile("" : "+v"(negm)); f32x16 o[4] = {}; bf16x8 qr[8]; char* QR_lds = lds + OFF_QR + wid * 4096;
;   const bf16* Qw = Qg + (row0 + q0 + wid * 32 + r32) * 768;
; #pragma unroll
;   for (int d0 = 0; d0 < 8; ++d0) qr[d0] = ld8(Qw + 128 * h + d0 * 16 + hi * 8);
;   { const bf16x8 t0 = ld8(Qw + 512 + 32 * h + hi * 8), t1 = ld8(Qw + 512 + 32 * h + 16 + hi * 8), t2 = ld8(Qw + 640 + 32 * h + hi * 8), t3 = ld8(Qw + 640 + 32 * h + 16 + hi * 8);
;     *(bf16x8*)(QR_lds + lane * 16) = t0; *(bf16x8*)(QR_lds + lane * 16 + 1024) = t1;
;     *(bf16x8*)(QR_lds + lane * 16 + 2048) = t2; *(bf16x8*)(QR_lds + lane * 16 + 3072) = t3; }
;   const int sr = tid >> 4, sc = (tid & 15) * 8, vst0 = v_st(sr, sc), vst1 = v_st(32 + sr, sc);
;   const int krow = 8 * wid + (lane & 7), kc8 = lane >> 3;
;   const int kwoff = (kc8 >> 1) * 2048 + (kc8 & 1) * 1024 + (krow >> 5) * 512 + (krow & 31) * 16;
;   const int vb0 = (int)(uintptr_t)V_lds + v_rd_base(lane);
;   const bf16* Vh = Vg + row0 * 512 + 128 * h;
;   const bf16* Kh = KNg + row0 * 512 + 128 * h;
;   const bf16* Rh = KRg + row0 * 64;
;   const unsigned kvoff = (unsigned)(sr * 512 + sc), knoff = (unsigned)(krow * 512 + kc8 * 8), kroff = (unsigned)(krow * 64 + kc8 * 8);
;   bf16x8 vs0, vs1, ks0, ks1, kr0;
;     ...
;   f32x16 pA0, pA1, pB0, pB1; float alA, alB; bf16x8 pa0, pa1, pa2, pa3;
;   const int NTt = (L + KVBLK - 1) / KVBLK, nv_last = L - (NTt - 1) * KVBLK;
;   if (wid >= 4) __builtin_amdgcn_s_setprio(1);
.LBB0_545:
	v_mov_b32_e32 v16, v183
	s_lshl_b32 s92, s4, 8
	v_readfirstlane_b32 s8, v16
	s_ashr_i32 s90, s8, 6
	s_lshl_b32 s0, s90, 12
	s_add_i32 s0, s0, 0
	s_and_b32 s91, s3, 3
	s_add_i32 s3, s0, 0x14800
	s_ashr_i32 s0, s92, 31
	s_add_u32 s1, s78, s92
	s_addc_u32 s4, s79, s0
	s_lshl_b32 s2, s90, 5
	s_ashr_i32 s5, s2, 31
	v_mov_b32_e32 v14, v1
	v_mov_b32_e32 v15, v1
	s_add_u32 s0, s2, s1
	v_and_b32_e32 v184, 31, v16
	v_mov_b32_e32 v0, v1
	v_mov_b32_e32 v2, v1
	v_mov_b32_e32 v3, v1
	v_mov_b32_e32 v4, v1
	v_mov_b32_e32 v5, v1
	v_mov_b32_e32 v6, v1
	v_mov_b32_e32 v7, v1
	v_mov_b32_e32 v8, v1
	v_mov_b32_e32 v9, v1
	v_mov_b32_e32 v10, v1
	v_mov_b32_e32 v11, v1
	v_mov_b32_e32 v12, v1
	v_mov_b32_e32 v13, v1
	v_mov_b64_e32 v[96:97], v[14:15]
	v_mov_b32_e32 v185, v1
	s_addc_u32 s1, s5, s4
	v_mov_b64_e32 v[94:95], v[12:13]
	v_mov_b64_e32 v[92:93], v[10:11]
	v_mov_b64_e32 v[90:91], v[8:9]
	v_mov_b64_e32 v[88:89], v[6:7]
	v_mov_b64_e32 v[86:87], v[4:5]
	v_mov_b64_e32 v[84:85], v[2:3]
	v_mov_b64_e32 v[82:83], v[0:1]
	v_lshl_add_u64 v[2:3], s[0:1], 0, v[184:185]
	v_mov_b64_e32 v[4:5], s[16:17]
	s_movk_i32 s4, 0x600
	v_mad_u64_u32 v[4:5], s[0:1], v2, s4, v[4:5]
	v_mov_b32_e32 v0, v5
	v_mad_u64_u32 v[2:3], s[0:1], v3, s4, v[0:1]
	v_bfe_u32 v196, v16, 5, 1
	v_mov_b32_e32 v5, v2
	s_lshl_b32 s70, s91, 8
	v_lshl_add_u64 v[2:3], v[4:5], 0, s[70:71]
	v_lshlrev_b32_e32 v188, 4, v196
	v_mov_b32_e32 v189, v1
	v_lshl_add_u64 v[14:15], v[2:3], 0, v[188:189]
	global_load_dwordx4 v[130:133], v[14:15], off
	global_load_dwordx4 v[134:137], v[14:15], off offset:32
	global_load_dwordx4 v[138:141], v[14:15], off offset:64
	global_load_dwordx4 v[142:145], v[14:15], off offset:96
	global_load_dwordx4 v[146:149], v[14:15], off offset:128
	global_load_dwordx4 v[150:153], v[14:15], off offset:160
	s_lshl_b32 s70, s91, 6
	v_lshl_add_u64 v[2:3], v[4:5], 0, s[70:71]
	v_lshl_add_u64 v[18:19], v[2:3], 0, v[188:189]
	global_load_dwordx4 v[2:5], v[18:19], off offset:1024
	global_load_dwordx4 v[6:9], v[18:19], off offset:1056
	global_load_dwordx4 v[10:13], v[18:19], off offset:1280
	s_nop 0
	global_load_dwordx4 v[18:21], v[18:19], off offset:1312
	s_nop 0
	global_load_dwordx4 v[154:157], v[14:15], off offset:192
	global_load_dwordx4 v[158:161], v[14:15], off offset:224
	v_and_b32_e32 v185, 63, v16
	v_lshlrev_b32_e32 v106, 4, v185
	s_lshl_b32 s0, s91, 7
	v_add_u32_e32 v189, s3, v106
	s_cmp_lt_i32 s90, 4
	s_waitcnt vmcnt(5)
	ds_write_b128 v189, v[2:5]
	s_waitcnt vmcnt(4)
	ds_write_b128 v189, v[6:9] offset:1024
	s_waitcnt vmcnt(3)
	ds_write_b128 v189, v[10:13] offset:2048
	s_waitcnt vmcnt(2)
	ds_write_b128 v189, v[18:21] offset:3072
	s_cbranch_scc1 .LBB0_547
	s_nop 0

; __device__ __forceinline__ int v_st(int k, int c) { const int kk = (k & ~0xC) | ((k & 4) << 1) | ((k & 8) >> 1); return ((kk >> 3) * 4 + (c >> 5)) * 512 + ((kk & 7) * 32 + (c & 31)) * 2; }
; __device__ __forceinline__ void attn_unit(const bf16* __restrict__ Qg, const bf16* __restrict__ KNg, const bf16* __restrict__ KRg, const bf16* __restrict__ Vg, bf16* __restrict__ AO, ...
;   int tid = threadIdx.x; asm volatile("" : "+v"(tid));
;   const int wid = __builtin_amdgcn_readfirstlane(tid >> 6), lane = tid & 63, r32 = lane & 31, hi = lane >> 5;
;   char* V_lds = lds + OFF_V; char* KN_lds = lds + OFF_KN; char* KR_lds = lds + OFF_KR;
;   float* ws = (float*)(lds + OFF_WS) + wid * 64; float* li_l = ws; float* al_l = ws + 32;
;   float mhat = 0.f, l_reg = 0; f32x16 negm = f32x16{}; asm volatile("" : "+v"(negm)); f32x16 o[4] = {}; bf16x8 qr[8]; char* QR_lds = lds + OFF_QR + wid * 4096;
;   const bf16* Qw = Qg + (row0 + q0 + wid * 32 + r32) * 768;
; #pragma unroll
;   for (int d0 = 0; d0 < 8; ++d0) qr[d0] = ld8(Qw + 128 * h + d0 * 16 + hi * 8);
;   { const bf16x8 t0 = ld8(Qw + 512 + 32 * h + hi * 8), t1 = ld8(Qw + 512 + 32 * h + 16 + hi * 8), t2 = ld8(Qw + 640 + 32 * h + hi * 8), t3 = ld8(Qw + 640 + 32 * h + 16 + hi * 8);
;     *(bf16x8*)(QR_lds + lane * 16) = t0; *(bf16x8*)(QR_lds + lane * 16 + 1024) = t1;
;     *(bf16x8*)(QR_lds + lane * 16 + 2048) = t2; *(bf16x8*)(QR_lds + lane * 16 + 3072) = t3; }
;   const int sr = tid >> 4, sc = (tid & 15) * 8, vst0 = v_st(sr, sc), vst1 = v_st(32 + sr, sc);
;   const int krow = 8 * wid + (lane & 7), kc8 = lane >> 3;
;   const int kwoff = (kc8 >> 1) * 2048 + (kc8 & 1) * 1024 + (krow >> 5) * 512 + (krow & 31) * 16;
;   const int vb0 = (int)(uintptr_t)V_lds + v_rd_base(lane);
;   const bf16* Vh = Vg + row0 * 512 + 128 * h;
;   const bf16* Kh = KNg + row0 * 512 + 128 * h;
;   const bf16* Rh = KRg + row0 * 64;
;   const unsigned kvoff = (unsigned)(sr * 512 + sc), knoff = (unsigned)(krow * 512 + kc8 * 8), kroff = (unsigned)(krow * 64 + kc8 * 8);
;   bf16x8 vs0, vs1, ks0, ks1, kr0;
;     ...
;   f32x16 pA0, pA1, pB0, pB1; float alA, alB; bf16x8 pa0, pa1, pa2, pa3;
;   const int NTt = (L + KVBLK - 1) / KVBLK, nv_last = L - (NTt - 1) * KVBLK;
;   if (wid >= 4) __builtin_amdgcn_s_setprio(1);
.LBB0_1360:
	v_mov_b32_e32 v16, v183
	s_lshl_b32 s0, s4, 8
	v_readfirstlane_b32 s6, v16
	s_ashr_i32 s94, s6, 6
	s_or_b32 s93, s0, 16
	s_lshl_b32 s0, s94, 12
	s_add_i32 s0, s0, 0
	s_and_b32 s92, s3, 3
	s_add_i32 s3, s0, 0x14800
	s_add_u32 s0, s84, s93
	s_addc_u32 s1, s85, 0
	s_lshl_b32 s2, s94, 5
	s_ashr_i32 s4, s2, 31
	v_mov_b32_e32 v14, v1
	v_mov_b32_e32 v15, v1
	s_add_u32 s0, s2, s0
	v_and_b32_e32 v22, 31, v16
	v_mov_b32_e32 v0, v1
	v_mov_b32_e32 v2, v1
	v_mov_b32_e32 v3, v1
	v_mov_b32_e32 v4, v1
	v_mov_b32_e32 v5, v1
	v_mov_b32_e32 v6, v1
	v_mov_b32_e32 v7, v1
	v_mov_b32_e32 v8, v1
	v_mov_b32_e32 v9, v1
	v_mov_b32_e32 v10, v1
	v_mov_b32_e32 v11, v1
	v_mov_b32_e32 v12, v1
	v_mov_b32_e32 v13, v1
	v_mov_b64_e32 v[96:97], v[14:15]
	v_mov_b32_e32 v23, v1
	s_addc_u32 s1, s4, s1
	v_mov_b64_e32 v[94:95], v[12:13]
	v_mov_b64_e32 v[92:93], v[10:11]
	v_mov_b64_e32 v[90:91], v[8:9]
	v_mov_b64_e32 v[88:89], v[6:7]
	v_mov_b64_e32 v[86:87], v[4:5]
	v_mov_b64_e32 v[84:85], v[2:3]
	v_mov_b64_e32 v[82:83], v[0:1]
	v_lshl_add_u64 v[2:3], s[0:1], 0, v[22:23]
	v_mov_b64_e32 v[4:5], s[70:71]
	s_movk_i32 s4, 0x600
	v_mad_u64_u32 v[4:5], s[0:1], v2, s4, v[4:5]
	v_mov_b32_e32 v0, v5
	v_mad_u64_u32 v[2:3], s[0:1], v3, s4, v[0:1]
	v_bfe_u32 v199, v16, 5, 1
	v_mov_b32_e32 v5, v2
	s_lshl_b32 s78, s92, 8
	v_lshl_add_u64 v[2:3], v[4:5], 0, s[78:79]
	v_lshlrev_b32_e32 v184, 4, v199
	v_mov_b32_e32 v185, v1
	v_lshl_add_u64 v[14:15], v[2:3], 0, v[184:185]
	global_load_dwordx4 v[130:133], v[14:15], off
	global_load_dwordx4 v[134:137], v[14:15], off offset:32
	global_load_dwordx4 v[138:141], v[14:15], off offset:64
	global_load_dwordx4 v[142:145], v[14:15], off offset:96
	global_load_dwordx4 v[146:149], v[14:15], off offset:128
	global_load_dwordx4 v[150:153], v[14:15], off offset:160
	s_lshl_b32 s0, s92, 6
	s_mov_b32 s1, s79
	v_lshl_add_u64 v[2:3], v[4:5], 0, s[0:1]
	v_lshl_add_u64 v[18:19], v[2:3], 0, v[184:185]
	global_load_dwordx4 v[2:5], v[18:19], off offset:1024
	global_load_dwordx4 v[6:9], v[18:19], off offset:1056
	global_load_dwordx4 v[10:13], v[18:19], off offset:1280
	s_nop 0
	global_load_dwordx4 v[18:21], v[18:19], off offset:1312
	s_nop 0
	global_load_dwordx4 v[154:157], v[14:15], off offset:192
	global_load_dwordx4 v[158:161], v[14:15], off offset:224
	v_and_b32_e32 v185, 63, v16
	v_lshlrev_b32_e32 v106, 4, v185
	s_lshl_b32 s0, s92, 7
	v_add_u32_e32 v201, s3, v106
	s_cmp_lt_i32 s94, 4
	s_waitcnt vmcnt(5)
	ds_write_b128 v201, v[2:5]
	s_waitcnt vmcnt(4)
	ds_write_b128 v201, v[6:9] offset:1024
	s_waitcnt vmcnt(3)
	ds_write_b128 v201, v[10:13] offset:2048
	s_waitcnt vmcnt(2)
	ds_write_b128 v201, v[18:21] offset:3072
	s_cbranch_scc1 .LBB0_1362
	s_nop 0
